# deferred P.V MFMAs interleaved with LDS-DMA issue (mp1) and bias-region logic (mp0); mp0 p0 row-sum adds deferred with them
# baseline (speedup 1.0000x reference)
.LBB0_622:
	v_add3_u32 v165, s57, v143, v163
	ds_read_b128 v[190:193], v165 offset:18432
	ds_read_b128 v[194:197], v165 offset:18448
	ds_read_b128 v[128:131], v165 offset:23040
	ds_read_b128 v[132:135], v165 offset:23056
	ds_read_b128 v[136:139], v165 offset:27648
	ds_read_b128 v[166:169], v165 offset:27664
	ds_read_b128 v[170:173], v165 offset:32256
	ds_read_b128 v[178:181], v165 offset:32272
	v_exp_f32_e32 v96, v96
	v_exp_f32_e32 v97, v97
	v_exp_f32_e32 v98, v98
	v_exp_f32_e32 v99, v99
	v_exp_f32_e32 v100, v100
	v_add_f32_e32 v198, v97, v96
	v_exp_f32_e32 v101, v101
	v_add_f32_e32 v198, v98, v198
	v_exp_f32_e32 v102, v102
	v_add_f32_e32 v198, v99, v198
	v_exp_f32_e32 v103, v103
	v_add_f32_e32 v198, v100, v198
	v_exp_f32_e32 v104, v104
	v_add_f32_e32 v198, v101, v198
	v_exp_f32_e32 v105, v105
	v_add_f32_e32 v198, v102, v198
	v_exp_f32_e32 v106, v106
	v_add_f32_e32 v198, v103, v198
	v_exp_f32_e32 v107, v107
	v_add_f32_e32 v198, v104, v198
	v_exp_f32_e32 v108, v108
	v_add_f32_e32 v198, v105, v198
	v_exp_f32_e32 v109, v109
	v_add_f32_e32 v198, v106, v198
	v_exp_f32_e32 v110, v110
	v_add_f32_e32 v198, v107, v198
	v_exp_f32_e32 v111, v111
	v_add_f32_e32 v198, v108, v198
	v_add_f32_e32 v198, v109, v198
	v_add_f32_e32 v198, v110, v198
	v_add_f32_e32 v198, v111, v198
	v_add_f32_e32 v157, v157, v198
	v_cvt_pk_bf16_f32 v96, v96, v97
	v_cvt_pk_bf16_f32 v97, v98, v99
	v_cvt_pk_bf16_f32 v98, v100, v101
	v_cvt_pk_bf16_f32 v99, v102, v103
	v_cvt_pk_bf16_f32 v100, v104, v105
	v_cvt_pk_bf16_f32 v101, v106, v107
	v_cvt_pk_bf16_f32 v102, v108, v109
	v_cvt_pk_bf16_f32 v103, v110, v111
	s_waitcnt lgkmcnt(7)
	v_mfma_f32_32x32x16_bf16 v[48:63], v[190:193], v[96:99], v[48:63]
	v_exp_f32_e32 v174, v80
	v_exp_f32_e32 v175, v81
	v_exp_f32_e32 v182, v82
	v_exp_f32_e32 v183, v83
	v_add_f32_e32 v80, v175, v174
	v_add_f32_e32 v80, v182, v80
	s_waitcnt lgkmcnt(5)
	v_mfma_f32_32x32x16_bf16 v[0:15], v[128:131], v[96:99], v[0:15]
	v_add_f32_e32 v80, v183, v80
	v_mfma_f32_32x32x16_bf16 v[48:63], v[194:197], v[100:103], v[48:63]
	v_exp_f32_e32 v128, v84
	v_exp_f32_e32 v129, v85
	v_exp_f32_e32 v130, v86
	v_exp_f32_e32 v131, v87
	v_add_f32_e32 v80, v128, v80
	v_add_f32_e32 v80, v129, v80
	v_add_f32_e32 v80, v130, v80
	s_waitcnt lgkmcnt(4)
	v_mfma_f32_32x32x16_bf16 v[0:15], v[132:135], v[100:103], v[0:15]
	v_add_f32_e32 v184, v131, v80
	ds_read_b128 v[80:83], v165 offset:18496
	ds_read_b128 v[84:87], v165 offset:18512
	ds_read_b128 v[104:107], v165 offset:23104
	ds_read_b128 v[108:111], v165 offset:23120
	s_waitcnt lgkmcnt(7)
	v_mfma_f32_32x32x16_bf16 v[32:47], v[136:139], v[96:99], v[32:47]
	v_exp_f32_e32 v132, v88
	v_exp_f32_e32 v133, v89
	v_exp_f32_e32 v134, v90
	v_exp_f32_e32 v135, v91
	v_add_f32_e32 v88, v132, v184
	v_add_f32_e32 v88, v133, v88
	v_add_f32_e32 v88, v134, v88
	s_waitcnt lgkmcnt(5)
	v_mfma_f32_32x32x16_bf16 v[16:31], v[170:173], v[96:99], v[16:31]
	v_add_f32_e32 v88, v135, v88
	v_exp_f32_e32 v96, v92
	v_mfma_f32_32x32x16_bf16 v[32:47], v[166:169], v[100:103], v[32:47]
	v_exp_f32_e32 v97, v93
	v_exp_f32_e32 v98, v94
	v_exp_f32_e32 v95, v95
	v_add_f32_e32 v88, v96, v88
	v_add_f32_e32 v88, v97, v88
	v_add_f32_e32 v88, v98, v88
	v_add_f32_e32 v88, v95, v88
	s_waitcnt lgkmcnt(4)
	v_mfma_f32_32x32x16_bf16 v[16:31], v[178:181], v[100:103], v[16:31]
	v_add_f32_e32 v157, v157, v88
	v_cvt_pk_bf16_f32 v88, v174, v175
	v_cvt_pk_bf16_f32 v89, v182, v183
	v_cvt_pk_bf16_f32 v90, v128, v129
	v_cvt_pk_bf16_f32 v91, v130, v131
	v_cvt_pk_bf16_f32 v92, v132, v133
	v_cvt_pk_bf16_f32 v93, v134, v135
	v_cvt_pk_bf16_f32 v94, v96, v97
	v_cvt_pk_bf16_f32 v95, v98, v95
	ds_read_b128 v[96:99], v165 offset:27712
	ds_read_b128 v[100:103], v165 offset:27728
	ds_read_b128 v[128:131], v165 offset:32320
	ds_read_b128 v[132:135], v165 offset:32336
	s_waitcnt lgkmcnt(7)
	v_mfma_f32_32x32x16_bf16 v[48:63], v[80:83], v[88:91], v[48:63]
	s_waitcnt lgkmcnt(5)
	v_mfma_f32_32x32x16_bf16 v[0:15], v[104:107], v[88:91], v[0:15]
	s_add_i32 s4, s9, 0x9000
	s_cmp_lg_u32 s9, 0x12000
	s_cselect_b32 s9, s4, 0
	v_mfma_f32_32x32x16_bf16 v[48:63], v[84:87], v[92:95], v[48:63]
	s_waitcnt lgkmcnt(4)
	v_mfma_f32_32x32x16_bf16 v[0:15], v[108:111], v[92:95], v[0:15]
	s_add_i32 s4, s56, 1
	s_cmp_lg_u32 s56, 2
	s_cselect_b32 s56, s4, 0
	s_add_i32 s8, s8, 1
	s_add_i32 s87, s87, 64
	s_cmpk_lg_i32 s87, 0xfc0
	s_waitcnt lgkmcnt(0)
	s_barrier
	s_cbranch_scc0 .Lv1p_flush
	s_add_i32 s57, s9, 0
	s_add_i32 s4, s57, s94
	v_add_u32_e32 v80, s4, v162
	v_add_u32_e32 v84, v80, v146
	ds_read_b128 v[80:83], v84
	ds_read_b128 v[220:223], v84 offset:32
	ds_read_b128 v[136:139], v84 offset:4608
	ds_read_b128 v[224:227], v84 offset:4640
	ds_read_b128 v[166:169], v84 offset:64
	ds_read_b128 v[170:173], v84 offset:96
	ds_read_b128 v[178:181], v84 offset:4672
	ds_read_b128 v[182:185], v84 offset:4704
	v_mfma_f32_32x32x16_bf16 v[32:47], v[96:99], v[88:91], v[32:47]
	s_cmp_gt_u32 s8, 61
	s_cselect_b64 s[78:79], -1, 0
	s_and_b64 vcc, exec, s[78:79]
	s_cbranch_vccnz .Lv1p_skipdma
	s_mul_i32 s16, s56, 0x9000
	s_add_i32 s17, s16, s35
	s_and_b64 s[80:81], s[54:55], exec
	s_cselect_b32 m0, s17, s82
	s_nop 0
	global_load_lds_dwordx4 v[240:241], off
	s_add_i32 s17, s16, s33
	s_and_b64 s[80:81], s[64:65], exec
	s_cselect_b32 m0, s17, s2
	v_lshl_add_u64 v[240:241], v[240:241], 0, v[200:201]
	global_load_lds_dwordx4 v[242:243], off
	v_mfma_f32_32x32x16_bf16 v[16:31], v[128:131], v[88:91], v[16:31]
	s_add_i32 s17, s16, s93
	s_and_b64 s[80:81], s[42:43], exec
	s_cselect_b32 m0, s17, s92
	v_lshl_add_u64 v[242:243], v[242:243], 0, v[202:203]
	global_load_lds_dwordx4 v[244:245], off
	s_add_i32 s17, s16, s45
	s_and_b64 s[80:81], s[24:25], exec
	s_cselect_b32 m0, s17, s97
	v_lshl_add_u64 v[244:245], v[244:245], 0, v[204:205]
	global_load_lds_dwordx4 v[246:247], off
	v_mfma_f32_32x32x16_bf16 v[32:47], v[100:103], v[92:95], v[32:47]
	s_add_i32 s17, s16, s59
	s_and_b64 s[80:81], s[70:71], exec
	s_cselect_b32 m0, s17, s27
	v_lshl_add_u64 v[246:247], v[246:247], 0, v[206:207]
	global_load_lds_dwordx4 v[248:249], off
	v_lshl_add_u64 v[248:249], v[248:249], 0, v[208:209]
	v_mfma_f32_32x32x16_bf16 v[16:31], v[132:135], v[92:95], v[16:31]
	s_branch .LBB0_625
.Lv1p_skipdma:
	v_mfma_f32_32x32x16_bf16 v[16:31], v[128:131], v[88:91], v[16:31]
	v_mfma_f32_32x32x16_bf16 v[32:47], v[100:103], v[92:95], v[32:47]
	v_mfma_f32_32x32x16_bf16 v[16:31], v[132:135], v[92:95], v[16:31]
	s_branch .LBB0_625

.LBB0_638:
	s_cmpk_eq_i32 s20, 0xfc0
	s_cbranch_scc1 .Lv2p_flush
	s_add_i32 s50, s44, 0
	v_add3_u32 v84, s50, v162, v146
	ds_read_b128 v[80:83], v84
	ds_read_b128 v[128:131], v84 offset:32
	ds_read_b128 v[132:135], v84 offset:4608
	ds_read_b128 v[136:139], v84 offset:4640
	ds_read_b128 v[140:143], v84 offset:64
	ds_read_b128 v[220:223], v84 offset:96
	ds_read_b128 v[224:227], v84 offset:4672
	ds_read_b128 v[228:231], v84 offset:4704
	v_mfma_f32_32x32x16_bf16 v[32:47], v[182:185], v[170:173], v[32:47]
	v_add_f32_e32 v96, v97, v96
	v_add_f32_e32 v96, v98, v96
	v_add_f32_e32 v96, v99, v96
	v_add_f32_e32 v96, v100, v96
	v_mfma_f32_32x32x16_bf16 v[16:31], v[190:193], v[170:173], v[16:31]
	v_add_f32_e32 v96, v101, v96
	v_add_f32_e32 v96, v102, v96
	v_add_f32_e32 v96, v103, v96
	v_add_f32_e32 v96, v104, v96
	s_add_i32 s51, s27, s20
	s_add_i32 s4, s51, 64
	s_cmpk_lt_i32 s4, 0xff42
	s_cselect_b32 s5, 1, 0
	s_cmpk_gt_i32 s4, 0x9e
	s_cselect_b32 s4, 2, s5
	s_cmp_eq_u32 s4, s32
	s_cbranch_scc1 .Lattn_negm_keep_1c
	s_mov_b32 s32, s4
	s_cmp_eq_u32 s4, 1
	s_cselect_b64 vcc, -1, 0
	s_cmp_eq_u32 s4, 2
	s_cselect_b64 s[4:5], -1, 0
	v_cndmask_b32_e64 v84, 0, v160, s[4:5]
	v_cndmask_b32_e32 v252, v84, v159, vcc
	v_sub_f32_e32 v84, v252, v156
	v_mov_b32_e32 v79, v84
	v_mov_b32_e32 v78, v84
	v_mov_b32_e32 v77, v84
	v_mov_b32_e32 v76, v84
	v_mov_b32_e32 v75, v84
	v_mov_b32_e32 v74, v84
	v_mov_b32_e32 v73, v84
	v_mov_b32_e32 v72, v84
	v_mov_b32_e32 v71, v84
	v_mov_b32_e32 v70, v84
	v_mov_b32_e32 v69, v84
	v_mov_b32_e32 v68, v84
	v_mov_b32_e32 v67, v84
	v_mov_b32_e32 v66, v84
	v_mov_b32_e32 v65, v84
	v_mov_b32_e32 v64, v84
.Lattn_negm_keep_1c:
	v_mfma_f32_32x32x16_bf16 v[32:47], v[186:189], v[178:181], v[32:47]
	v_add_f32_e32 v96, v105, v96
	v_add_f32_e32 v96, v106, v96
	v_add_f32_e32 v96, v107, v96
	v_add_f32_e32 v96, v108, v96
	v_mfma_f32_32x32x16_bf16 v[16:31], v[194:197], v[178:181], v[16:31]
	v_add_f32_e32 v96, v109, v96
	v_add_f32_e32 v96, v110, v96
	v_add_f32_e32 v96, v111, v96
	v_add_f32_e32 v96, v157, v96
	v_add_f32_e32 v157, v96, v251
	s_branch .Lv2p_body2

.Lattn_negm_keep_1:
.Lv2p_body2:
	s_addk_i32 s51, 0xffa1
	s_cmp_lt_u32 s51, 0xfffffea3
	s_nop 0
	s_waitcnt lgkmcnt(7)
	v_mfma_f32_32x32x16_bf16 v[96:111], v[80:83], v[112:115], v[64:79]
	s_waitcnt lgkmcnt(5)
	v_mfma_f32_32x32x16_bf16 v[80:95], v[132:135], v[112:115], v[64:79]
	v_mfma_f32_32x32x16_bf16 v[96:111], v[128:131], v[116:119], v[96:111]
	s_waitcnt lgkmcnt(4)
	v_mfma_f32_32x32x16_bf16 v[80:95], v[136:139], v[116:119], v[80:95]
	s_waitcnt lgkmcnt(3)
	v_mfma_f32_32x32x16_bf16 v[96:111], v[140:143], v[120:123], v[96:111]
	s_waitcnt lgkmcnt(1)
	v_mfma_f32_32x32x16_bf16 v[80:95], v[224:227], v[120:123], v[80:95]
	v_mfma_f32_32x32x16_bf16 v[96:111], v[220:223], v[124:127], v[96:111]
	s_waitcnt lgkmcnt(0)
	v_mfma_f32_32x32x16_bf16 v[80:95], v[228:231], v[124:127], v[80:95]
	s_cbranch_scc1 .LBB0_641
	v_add_u32_e32 v178, s20, v166
	s_mov_b32 s51, 0x20380
	v_lshl_add_u32 v250, v178, 2, s51
	ds_read2_b32 v[128:129], v250 offset0:0 offset1:1
	ds_read2_b32 v[132:133], v250 offset0:2 offset1:3
	ds_read2_b32 v[136:137], v250 offset0:4 offset1:5
	ds_read2_b32 v[140:141], v250 offset0:6 offset1:7
	ds_read2_b32 v[168:169], v250 offset0:8 offset1:9
	ds_read2_b32 v[172:173], v250 offset0:10 offset1:11
	ds_read2_b32 v[178:179], v250 offset0:12 offset1:13
	ds_read2_b32 v[182:183], v250 offset0:14 offset1:15
	ds_read2_b32 v[130:131], v250 offset0:32 offset1:33
	ds_read2_b32 v[134:135], v250 offset0:34 offset1:35
	ds_read2_b32 v[138:139], v250 offset0:36 offset1:37
	ds_read2_b32 v[142:143], v250 offset0:38 offset1:39
	ds_read2_b32 v[170:171], v250 offset0:40 offset1:41
	ds_read2_b32 v[174:175], v250 offset0:42 offset1:43
	ds_read2_b32 v[180:181], v250 offset0:44 offset1:45
	ds_read2_b32 v[184:185], v250 offset0:46 offset1:47
	s_waitcnt lgkmcnt(0)
	v_pk_add_f32 v[110:111], v[110:111], v[182:183]
	v_pk_add_f32 v[108:109], v[108:109], v[178:179]
	v_pk_add_f32 v[106:107], v[106:107], v[172:173]
	v_pk_add_f32 v[104:105], v[104:105], v[168:169]
	v_pk_add_f32 v[102:103], v[102:103], v[140:141]
	v_pk_add_f32 v[100:101], v[100:101], v[136:137]
	v_pk_add_f32 v[98:99], v[98:99], v[132:133]
	v_pk_add_f32 v[96:97], v[96:97], v[128:129]
	v_pk_add_f32 v[94:95], v[94:95], v[184:185]
	v_pk_add_f32 v[92:93], v[92:93], v[180:181]
	v_pk_add_f32 v[90:91], v[90:91], v[174:175]
	v_pk_add_f32 v[88:89], v[88:89], v[170:171]
	v_pk_add_f32 v[86:87], v[86:87], v[142:143]
	v_pk_add_f32 v[84:85], v[84:85], v[138:139]
	v_pk_add_f32 v[82:83], v[82:83], v[134:135]
	v_pk_add_f32 v[80:81], v[80:81], v[130:131]

.LBB0_645:
	s_waitcnt lgkmcnt(7)
	v_mfma_f32_32x32x16_bf16 v[48:63], v[128:131], v[170:173], v[48:63]
	v_add_f32_e32 v80, v81, v80
	v_add_f32_e32 v80, v82, v80
	v_add_f32_e32 v80, v83, v80
	v_add_f32_e32 v80, v84, v80
	s_waitcnt lgkmcnt(5)
	v_mfma_f32_32x32x16_bf16 v[0:15], v[136:139], v[170:173], v[0:15]
	v_add_f32_e32 v80, v85, v80
	v_add_f32_e32 v80, v86, v80
	v_add_f32_e32 v80, v87, v80
	v_add_f32_e32 v80, v88, v80
	s_add_i32 s4, s44, 0x9000
	s_cmp_lg_u32 s44, 0x12000
	s_cselect_b32 s44, s4, 0
	s_add_i32 s4, s45, 1
	v_mfma_f32_32x32x16_bf16 v[48:63], v[132:135], v[178:181], v[48:63]
	v_add_f32_e32 v80, v89, v80
	v_add_f32_e32 v80, v90, v80
	v_add_f32_e32 v80, v91, v80
	v_add_f32_e32 v80, v92, v80
	s_waitcnt lgkmcnt(4)
	v_mfma_f32_32x32x16_bf16 v[0:15], v[140:143], v[178:181], v[0:15]
	v_add_f32_e32 v80, v93, v80
	v_add_f32_e32 v80, v94, v80
	v_add_f32_e32 v251, v95, v80
	s_cmp_lg_u32 s45, 2
	s_cselect_b32 s45, s4, 0
	s_add_i32 s33, s33, 1
	s_add_u32 s10, s10, 0x60000
	s_addc_u32 s11, s11, 0
	s_add_i32 s20, s20, 64
	s_mov_b64 s[60:61], -1
	s_and_b64 vcc, exec, s[50:51]
	s_cbranch_vccz .LBB0_647
	s_waitcnt vmcnt(0) lgkmcnt(0)
	s_barrier
	s_mov_b64 s[60:61], 0

.Lv2p_flush:
	v_mfma_f32_32x32x16_bf16 v[32:47], v[182:185], v[170:173], v[32:47]
	v_add_f32_e32 v96, v97, v96
	v_add_f32_e32 v96, v98, v96
	v_add_f32_e32 v96, v99, v96
	v_add_f32_e32 v96, v100, v96
	v_mfma_f32_32x32x16_bf16 v[16:31], v[190:193], v[170:173], v[16:31]
	v_add_f32_e32 v96, v101, v96
	v_add_f32_e32 v96, v102, v96
	v_add_f32_e32 v96, v103, v96
	v_add_f32_e32 v96, v104, v96
	v_mfma_f32_32x32x16_bf16 v[32:47], v[186:189], v[178:181], v[32:47]
	v_add_f32_e32 v96, v105, v96
	v_add_f32_e32 v96, v106, v96
	v_add_f32_e32 v96, v107, v96
	v_add_f32_e32 v96, v108, v96
	v_mfma_f32_32x32x16_bf16 v[16:31], v[194:197], v[178:181], v[16:31]
	v_add_f32_e32 v96, v109, v96
	v_add_f32_e32 v96, v110, v96
	v_add_f32_e32 v96, v111, v96
	v_add_f32_e32 v96, v157, v96
	v_add_f32_e32 v157, v96, v251

.LBB0_683:
	v_add3_u32 v165, s57, v143, v163
	ds_read_b128 v[190:193], v165 offset:18432
	ds_read_b128 v[194:197], v165 offset:18448
	ds_read_b128 v[128:131], v165 offset:23040
	ds_read_b128 v[132:135], v165 offset:23056
	ds_read_b128 v[136:139], v165 offset:27648
	ds_read_b128 v[166:169], v165 offset:27664
	ds_read_b128 v[170:173], v165 offset:32256
	ds_read_b128 v[178:181], v165 offset:32272
	v_exp_f32_e32 v96, v96
	v_exp_f32_e32 v97, v97
	v_exp_f32_e32 v98, v98
	v_exp_f32_e32 v99, v99
	v_exp_f32_e32 v100, v100
	v_add_f32_e32 v198, v97, v96
	v_exp_f32_e32 v101, v101
	v_add_f32_e32 v198, v98, v198
	v_exp_f32_e32 v102, v102
	v_add_f32_e32 v198, v99, v198
	v_exp_f32_e32 v103, v103
	v_add_f32_e32 v198, v100, v198
	v_exp_f32_e32 v104, v104
	v_add_f32_e32 v198, v101, v198
	v_exp_f32_e32 v105, v105
	v_add_f32_e32 v198, v102, v198
	v_exp_f32_e32 v106, v106
	v_add_f32_e32 v198, v103, v198
	v_exp_f32_e32 v107, v107
	v_add_f32_e32 v198, v104, v198
	v_exp_f32_e32 v108, v108
	v_add_f32_e32 v198, v105, v198
	v_exp_f32_e32 v109, v109
	v_add_f32_e32 v198, v106, v198
	v_exp_f32_e32 v110, v110
	v_add_f32_e32 v198, v107, v198
	v_exp_f32_e32 v111, v111
	v_add_f32_e32 v198, v108, v198
	v_add_f32_e32 v198, v109, v198
	v_add_f32_e32 v198, v110, v198
	v_add_f32_e32 v198, v111, v198
	v_add_f32_e32 v157, v157, v198
	v_cvt_pk_bf16_f32 v96, v96, v97
	v_cvt_pk_bf16_f32 v97, v98, v99
	v_cvt_pk_bf16_f32 v98, v100, v101
	v_cvt_pk_bf16_f32 v99, v102, v103
	v_cvt_pk_bf16_f32 v100, v104, v105
	v_cvt_pk_bf16_f32 v101, v106, v107
	v_cvt_pk_bf16_f32 v102, v108, v109
	v_cvt_pk_bf16_f32 v103, v110, v111
	s_waitcnt lgkmcnt(7)
	v_mfma_f32_32x32x16_bf16 v[48:63], v[190:193], v[96:99], v[48:63]
	v_exp_f32_e32 v174, v80
	v_exp_f32_e32 v175, v81
	v_exp_f32_e32 v182, v82
	v_exp_f32_e32 v183, v83
	v_add_f32_e32 v80, v175, v174
	v_add_f32_e32 v80, v182, v80
	s_waitcnt lgkmcnt(5)
	v_mfma_f32_32x32x16_bf16 v[0:15], v[128:131], v[96:99], v[0:15]
	v_add_f32_e32 v80, v183, v80
	v_mfma_f32_32x32x16_bf16 v[48:63], v[194:197], v[100:103], v[48:63]
	v_exp_f32_e32 v128, v84
	v_exp_f32_e32 v129, v85
	v_exp_f32_e32 v130, v86
	v_exp_f32_e32 v131, v87
	v_add_f32_e32 v80, v128, v80
	v_add_f32_e32 v80, v129, v80
	v_add_f32_e32 v80, v130, v80
	s_waitcnt lgkmcnt(4)
	v_mfma_f32_32x32x16_bf16 v[0:15], v[132:135], v[100:103], v[0:15]
	v_add_f32_e32 v184, v131, v80
	ds_read_b128 v[80:83], v165 offset:18496
	ds_read_b128 v[84:87], v165 offset:18512
	ds_read_b128 v[104:107], v165 offset:23104
	ds_read_b128 v[108:111], v165 offset:23120
	s_waitcnt lgkmcnt(7)
	v_mfma_f32_32x32x16_bf16 v[32:47], v[136:139], v[96:99], v[32:47]
	v_exp_f32_e32 v132, v88
	v_exp_f32_e32 v133, v89
	v_exp_f32_e32 v134, v90
	v_exp_f32_e32 v135, v91
	v_add_f32_e32 v88, v132, v184
	v_add_f32_e32 v88, v133, v88
	v_add_f32_e32 v88, v134, v88
	s_waitcnt lgkmcnt(5)
	v_mfma_f32_32x32x16_bf16 v[16:31], v[170:173], v[96:99], v[16:31]
	v_add_f32_e32 v88, v135, v88
	v_exp_f32_e32 v96, v92
	v_mfma_f32_32x32x16_bf16 v[32:47], v[166:169], v[100:103], v[32:47]
	v_exp_f32_e32 v97, v93
	v_exp_f32_e32 v98, v94
	v_exp_f32_e32 v95, v95
	v_add_f32_e32 v88, v96, v88
	v_add_f32_e32 v88, v97, v88
	v_add_f32_e32 v88, v98, v88
	v_add_f32_e32 v88, v95, v88
	s_waitcnt lgkmcnt(4)
	v_mfma_f32_32x32x16_bf16 v[16:31], v[178:181], v[100:103], v[16:31]
	v_add_f32_e32 v157, v157, v88
	v_cvt_pk_bf16_f32 v88, v174, v175
	v_cvt_pk_bf16_f32 v89, v182, v183
	v_cvt_pk_bf16_f32 v90, v128, v129
	v_cvt_pk_bf16_f32 v91, v130, v131
	v_cvt_pk_bf16_f32 v92, v132, v133
	v_cvt_pk_bf16_f32 v93, v134, v135
	v_cvt_pk_bf16_f32 v94, v96, v97
	v_cvt_pk_bf16_f32 v95, v98, v95
	ds_read_b128 v[96:99], v165 offset:27712
	ds_read_b128 v[100:103], v165 offset:27728
	ds_read_b128 v[128:131], v165 offset:32320
	ds_read_b128 v[132:135], v165 offset:32336
	s_waitcnt lgkmcnt(7)
	v_mfma_f32_32x32x16_bf16 v[48:63], v[80:83], v[88:91], v[48:63]
	s_waitcnt lgkmcnt(5)
	v_mfma_f32_32x32x16_bf16 v[0:15], v[104:107], v[88:91], v[0:15]
	s_add_i32 s4, s9, 0x9000
	s_cmp_lg_u32 s9, 0x12000
	s_cselect_b32 s9, s4, 0
	s_add_i32 s4, s56, 1
	v_mfma_f32_32x32x16_bf16 v[48:63], v[84:87], v[92:95], v[48:63]
	s_waitcnt lgkmcnt(4)
	v_mfma_f32_32x32x16_bf16 v[0:15], v[108:111], v[92:95], v[0:15]
	s_cmp_lg_u32 s56, 2
	s_cselect_b32 s56, s4, 0
	s_add_i32 s8, s8, 1
	s_add_u32 s10, s10, 0x60000
	s_addc_u32 s11, s11, 0
	s_add_i32 s58, s58, 64
	s_cmpk_lg_i32 s58, 0x7c0
	s_waitcnt lgkmcnt(0)
	s_barrier
	s_cbranch_scc0 .Lv1s_flush
	s_add_i32 s57, s9, 0
	s_add_i32 s4, s57, s94
	v_add_u32_e32 v80, s4, v162
	v_add_u32_e32 v84, v80, v146
	ds_read_b128 v[80:83], v84
	ds_read_b128 v[220:223], v84 offset:32
	ds_read_b128 v[136:139], v84 offset:4608
	ds_read_b128 v[224:227], v84 offset:4640
	ds_read_b128 v[166:169], v84 offset:64
	ds_read_b128 v[170:173], v84 offset:96
	ds_read_b128 v[178:181], v84 offset:4672
	ds_read_b128 v[182:185], v84 offset:4704
	v_mfma_f32_32x32x16_bf16 v[32:47], v[96:99], v[88:91], v[32:47]
	s_cmp_gt_u32 s8, 29
	s_cselect_b64 s[78:79], -1, 0
	s_and_b64 vcc, exec, s[78:79]
	s_cbranch_vccnz .Lv1s_skipdma
	s_mul_i32 vcc_lo, s56, 0x9000
	s_add_i32 vcc_hi, vcc_lo, s35
	s_and_b64 s[80:81], s[54:55], exec
	s_cselect_b32 m0, vcc_hi, s82
	s_nop 0
	global_load_lds_dwordx4 v[240:241], off
	s_add_i32 vcc_hi, vcc_lo, s33
	s_and_b64 s[80:81], s[64:65], exec
	s_cselect_b32 m0, vcc_hi, s2
	v_lshl_add_u64 v[240:241], v[240:241], 0, v[200:201]
	global_load_lds_dwordx4 v[242:243], off
	v_mfma_f32_32x32x16_bf16 v[16:31], v[128:131], v[88:91], v[16:31]
	s_add_i32 vcc_hi, vcc_lo, s93
	s_and_b64 s[80:81], s[42:43], exec
	s_cselect_b32 m0, vcc_hi, s92
	v_lshl_add_u64 v[242:243], v[242:243], 0, v[202:203]
	global_load_lds_dwordx4 v[244:245], off
	s_add_i32 vcc_hi, vcc_lo, s45
	s_and_b64 s[80:81], s[24:25], exec
	s_cselect_b32 m0, vcc_hi, s97
	v_lshl_add_u64 v[244:245], v[244:245], 0, v[204:205]
	global_load_lds_dwordx4 v[246:247], off
	v_mfma_f32_32x32x16_bf16 v[32:47], v[100:103], v[92:95], v[32:47]
	s_add_i32 vcc_hi, vcc_lo, s59
	s_and_b64 s[80:81], s[70:71], exec
	s_cselect_b32 m0, vcc_hi, s86
	v_lshl_add_u64 v[246:247], v[246:247], 0, v[206:207]
	global_load_lds_dwordx4 v[248:249], off
	v_lshl_add_u64 v[248:249], v[248:249], 0, v[208:209]
	v_mfma_f32_32x32x16_bf16 v[16:31], v[132:135], v[92:95], v[16:31]
	s_branch .LBB0_686

.LBB0_699:
	s_cmpk_eq_i32 s20, 0x7c0
	s_cbranch_scc1 .Lv2s_flush
	s_add_i32 s56, s44, 0
	v_add3_u32 v84, s56, v162, v146
	ds_read_b128 v[80:83], v84
	ds_read_b128 v[128:131], v84 offset:32
	ds_read_b128 v[132:135], v84 offset:4608
	ds_read_b128 v[136:139], v84 offset:4640
	ds_read_b128 v[140:143], v84 offset:64
	ds_read_b128 v[220:223], v84 offset:96
	ds_read_b128 v[224:227], v84 offset:4672
	ds_read_b128 v[228:231], v84 offset:4704
	v_mfma_f32_32x32x16_bf16 v[32:47], v[182:185], v[170:173], v[32:47]
	v_add_f32_e32 v96, v97, v96
	v_add_f32_e32 v96, v98, v96
	v_add_f32_e32 v96, v99, v96
	v_add_f32_e32 v96, v100, v96
	v_mfma_f32_32x32x16_bf16 v[16:31], v[190:193], v[170:173], v[16:31]
	v_add_f32_e32 v96, v101, v96
	v_add_f32_e32 v96, v102, v96
	v_add_f32_e32 v96, v103, v96
	v_add_f32_e32 v96, v104, v96
	s_add_i32 s16, s27, s20
	s_add_i32 s4, s16, 64
	s_cmpk_lt_i32 s4, 0xff42
	s_cselect_b32 s5, 1, 0
	s_cmpk_gt_i32 s4, 0x9e
	s_cselect_b32 s4, 2, s5
	s_cmp_eq_u32 s4, s32
	s_cbranch_scc1 .Lattn_negm_keep_3c
	s_mov_b32 s32, s4
	s_cmp_eq_u32 s4, 1
	s_cselect_b64 vcc, -1, 0
	s_cmp_eq_u32 s4, 2
	s_cselect_b64 s[4:5], -1, 0
	v_cndmask_b32_e64 v84, 0, v160, s[4:5]
	v_cndmask_b32_e32 v252, v84, v159, vcc
	v_sub_f32_e32 v84, v252, v156
	v_mov_b32_e32 v79, v84
	v_mov_b32_e32 v78, v84
	v_mov_b32_e32 v77, v84
	v_mov_b32_e32 v76, v84
	v_mov_b32_e32 v75, v84
	v_mov_b32_e32 v74, v84
	v_mov_b32_e32 v73, v84
	v_mov_b32_e32 v72, v84
	v_mov_b32_e32 v71, v84
	v_mov_b32_e32 v70, v84
	v_mov_b32_e32 v69, v84
	v_mov_b32_e32 v68, v84
	v_mov_b32_e32 v67, v84
	v_mov_b32_e32 v66, v84
	v_mov_b32_e32 v65, v84
	v_mov_b32_e32 v64, v84

.Lattn_negm_keep_3:
.Lv2s_body2:
	s_addk_i32 s16, 0xffa1
	s_cmp_lt_u32 s16, 0xfffffea3
	s_nop 0
	s_waitcnt lgkmcnt(7)
	v_mfma_f32_32x32x16_bf16 v[96:111], v[80:83], v[112:115], v[64:79]
	s_waitcnt lgkmcnt(5)
	v_mfma_f32_32x32x16_bf16 v[80:95], v[132:135], v[112:115], v[64:79]
	v_mfma_f32_32x32x16_bf16 v[96:111], v[128:131], v[116:119], v[96:111]
	s_waitcnt lgkmcnt(4)
	v_mfma_f32_32x32x16_bf16 v[80:95], v[136:139], v[116:119], v[80:95]
	s_waitcnt lgkmcnt(3)
	v_mfma_f32_32x32x16_bf16 v[96:111], v[140:143], v[120:123], v[96:111]
	s_waitcnt lgkmcnt(1)
	v_mfma_f32_32x32x16_bf16 v[80:95], v[224:227], v[120:123], v[80:95]
	v_mfma_f32_32x32x16_bf16 v[96:111], v[220:223], v[124:127], v[96:111]
	s_waitcnt lgkmcnt(0)
	v_mfma_f32_32x32x16_bf16 v[80:95], v[228:231], v[124:127], v[80:95]
	s_cbranch_scc1 .LBB0_702
	v_add_u32_e32 v178, s20, v166
	s_mov_b32 s57, 0x20380
	v_lshl_add_u32 v250, v178, 2, s57
	ds_read2_b32 v[128:129], v250 offset0:0 offset1:1
	ds_read2_b32 v[132:133], v250 offset0:2 offset1:3
	ds_read2_b32 v[136:137], v250 offset0:4 offset1:5
	ds_read2_b32 v[140:141], v250 offset0:6 offset1:7
	ds_read2_b32 v[168:169], v250 offset0:8 offset1:9
	ds_read2_b32 v[172:173], v250 offset0:10 offset1:11
	ds_read2_b32 v[178:179], v250 offset0:12 offset1:13
	ds_read2_b32 v[182:183], v250 offset0:14 offset1:15
	ds_read2_b32 v[130:131], v250 offset0:32 offset1:33
	ds_read2_b32 v[134:135], v250 offset0:34 offset1:35
	ds_read2_b32 v[138:139], v250 offset0:36 offset1:37
	ds_read2_b32 v[142:143], v250 offset0:38 offset1:39
	ds_read2_b32 v[170:171], v250 offset0:40 offset1:41
	ds_read2_b32 v[174:175], v250 offset0:42 offset1:43
	ds_read2_b32 v[180:181], v250 offset0:44 offset1:45
	ds_read2_b32 v[184:185], v250 offset0:46 offset1:47
	s_waitcnt lgkmcnt(0)
	v_pk_add_f32 v[110:111], v[110:111], v[182:183]
	v_pk_add_f32 v[108:109], v[108:109], v[178:179]
	v_pk_add_f32 v[106:107], v[106:107], v[172:173]
	v_pk_add_f32 v[104:105], v[104:105], v[168:169]
	v_pk_add_f32 v[102:103], v[102:103], v[140:141]
	v_pk_add_f32 v[100:101], v[100:101], v[136:137]
	v_pk_add_f32 v[98:99], v[98:99], v[132:133]
	v_pk_add_f32 v[96:97], v[96:97], v[128:129]
	v_pk_add_f32 v[94:95], v[94:95], v[184:185]
	v_pk_add_f32 v[92:93], v[92:93], v[180:181]
	v_pk_add_f32 v[90:91], v[90:91], v[174:175]
	v_pk_add_f32 v[88:89], v[88:89], v[170:171]
	v_pk_add_f32 v[86:87], v[86:87], v[142:143]
	v_pk_add_f32 v[84:85], v[84:85], v[138:139]
	v_pk_add_f32 v[82:83], v[82:83], v[134:135]
	v_pk_add_f32 v[80:81], v[80:81], v[130:131]

.LBB0_706:
	s_waitcnt lgkmcnt(7)
	v_mfma_f32_32x32x16_bf16 v[48:63], v[128:131], v[170:173], v[48:63]
	v_add_f32_e32 v80, v81, v80
	v_add_f32_e32 v80, v82, v80
	v_add_f32_e32 v80, v83, v80
	v_add_f32_e32 v80, v84, v80
	s_waitcnt lgkmcnt(5)
	v_mfma_f32_32x32x16_bf16 v[0:15], v[136:139], v[170:173], v[0:15]
	v_add_f32_e32 v80, v85, v80
	v_add_f32_e32 v80, v86, v80
	v_add_f32_e32 v80, v87, v80
	v_add_f32_e32 v80, v88, v80
	s_add_i32 s4, s44, 0x9000
	s_cmp_lg_u32 s44, 0x12000
	s_cselect_b32 s44, s4, 0
	v_mfma_f32_32x32x16_bf16 v[48:63], v[132:135], v[178:181], v[48:63]
	v_add_f32_e32 v80, v89, v80
	v_add_f32_e32 v80, v90, v80
	v_add_f32_e32 v80, v91, v80
	v_add_f32_e32 v80, v92, v80
	s_waitcnt lgkmcnt(4)
	v_mfma_f32_32x32x16_bf16 v[0:15], v[140:143], v[178:181], v[0:15]
	v_add_f32_e32 v80, v93, v80
	v_add_f32_e32 v80, v94, v80
	v_add_f32_e32 v251, v95, v80
	s_add_i32 s4, s45, 1
	s_cmp_lg_u32 s45, 2
	s_cselect_b32 s45, s4, 0
	s_add_i32 s33, s33, 1
	s_add_i32 s20, s20, 64
	s_mov_b64 s[62:63], -1
	s_and_b64 vcc, exec, s[60:61]
	s_cbranch_vccz .LBB0_708
	s_waitcnt vmcnt(0) lgkmcnt(0)
	s_barrier
	s_mov_b64 s[62:63], 0
